# nt policy also on the prep phase's bf16 stores and the SGU sv-tile loads (whole lines, read once)
# baseline (speedup 1.0000x reference)
; __device__ __forceinline__ unsigned cvt_pk_bf16(float lo, float hi) { unsigned r; asm volatile("v_cvt_pk_bf16_f32 %0, %1, %2" : "=v"(r) : "v"(lo), "v"(hi)); return r; }
; PHASE_FN void phase_prep(const Params& p, float* ldsf) {
;     ...
;           { const int nn = tid >> 3, ks = (tid & 7) * 8; float v[8];
; #pragma unroll
;             for (int i = 0; i < 8; ++i) v[i] = tile[(ks + i) * 65 + nn];
;             u32x4 o; o.x = cvt_pk_bf16(v[0], v[1]); o.y = cvt_pk_bf16(v[2], v[3]); o.z = cvt_pk_bf16(v[4], v[5]); o.w = cvt_pk_bf16(v[6], v[7]);
;             *(u32x4*)(w.dst + (size_t)(w.n0 + nn) * w.K + w.k0 + ks) = o; }
.LBB0_38:
	v_lshlrev_b32_e32 v3, 2, v15
	s_waitcnt lgkmcnt(0)
	s_barrier
	v_add3_u32 v3, s50, v3, v23
	ds_read2_b32 v[18:19], v3 offset1:65
	ds_read2_b32 v[20:21], v3 offset0:130 offset1:195
	v_add_u32_e32 v3, 0x400, v3
	ds_read2_b32 v[26:27], v3 offset0:4 offset1:69
	ds_read2_b32 v[28:29], v3 offset0:134 offset1:199
	v_add_u32_e32 v3, s3, v15
	s_waitcnt lgkmcnt(3)
	v_cvt_pk_bf16_f32 v18, v18, v19
	s_waitcnt lgkmcnt(2)
	v_cvt_pk_bf16_f32 v19, v20, v21
	s_waitcnt lgkmcnt(1)
	v_cvt_pk_bf16_f32 v20, v26, v27
	v_mad_u64_u32 v[26:27], s[14:15], v3, s7, 0
	s_waitcnt lgkmcnt(0)
	v_cvt_pk_bf16_f32 v21, v28, v29
	v_ashrrev_i32_e32 v5, 31, v3
	v_mov_b32_e32 v28, v27
	v_mad_u64_u32 v[28:29], s[14:15], v5, s7, v[28:29]
	v_mov_b32_e32 v27, v28
	v_lshl_add_u64 v[26:27], v[26:27], 1, s[4:5]
	s_ashr_i32 s7, s6, 31
	v_lshl_add_u64 v[26:27], s[6:7], 1, v[26:27]
	v_mov_b32_e32 v17, v2
	v_lshl_add_u64 v[26:27], v[26:27], 0, v[16:17]
	s_xor_b32 s43, s43, 1
	s_add_i32 s39, s39, s40
	s_add_i32 s41, s41, s42
	s_andn2_b64 vcc, exec, s[10:11]
	s_mov_b64 s[4:5], s[12:13]
	s_mov_b32 s7, s53
	s_mov_b32 s3, s51
	s_mov_b32 s6, s52
	global_store_dwordx4 v[26:27], v[18:21], off nt
	s_cbranch_vccz .LBB0_68

; __device__ __forceinline__ unsigned cvt_pk_bf16(float lo, float hi) { unsigned r; asm volatile("v_cvt_pk_bf16_f32 %0, %1, %2" : "=v"(r) : "v"(lo), "v"(hi)); return r; }
; PHASE_FN void phase_prep(const Params& p, float* ldsf) {
;     ...
;     { bf16_t* wsb = (bf16_t*)(ws + WS_WSB);
;       for (int i = (bx * 512 + tid) * 4; i < DEPTH * 4 * 128 * 128; i += G * 512 * 4) { const f32x4 v = *(const f32x4*)(p.w_s + i); u32x2 w; w.x = cvt_pk_bf16(v[0], v[1]); w.y = cvt_pk_bf16(v[2], v[3]); *(u32x2*)(wsb + i) = w; } }
.LBB0_70:
	v_add_u32_e32 v2, s6, v2
	global_load_dwordx4 v[8:11], v[4:5], off nt
	v_cmp_lt_i32_e32 vcc, s3, v2
	v_lshl_add_u64 v[4:5], v[4:5], 0, s[10:11]
	s_or_b64 s[14:15], vcc, s[14:15]
	s_waitcnt vmcnt(0)
	v_cvt_pk_bf16_f32 v8, v8, v9
	v_cvt_pk_bf16_f32 v9, v10, v11
	global_store_dwordx2 v[6:7], v[8:9], off nt
	v_lshl_add_u64 v[6:7], v[6:7], 0, s[12:13]
	s_andn2_b64 exec, exec, s[14:15]
	s_cbranch_execnz .LBB0_70

; __device__ __forceinline__ unsigned cvt_pk_bf16(float lo, float hi) { unsigned r; asm volatile("v_cvt_pk_bf16_f32 %0, %1, %2" : "=v"(r) : "v"(lo), "v"(hi)); return r; }
; PHASE_FN void phase_prep(const Params& p, float* ldsf) {
;     ...
;       for (int r = bx * 8 + wid; r < T; r += G * 8) { const float* xr = p.x + (size_t)r * D; float ss = 0.f;
; #pragma unroll
;           for (int i = 0; i < 4; ++i) { const int c = i * 256 + lane * 4; const f32x4 v = *(const f32x4*)(xr + c); ss += (v[0] * v[0] + v[1] * v[1]) + (v[2] * v[2] + v[3] * v[3]);
;               u32x2 w; w.x = cvt_pk_bf16(v[0], v[1]); w.y = cvt_pk_bf16(v[2], v[3]); *(u32x2*)(xb + (size_t)r * D + c) = w; }
; #pragma unroll
;           for (int o = 32; o >= 1; o >>= 1) ss += __shfl_xor(ss, o);
;           if (lane < 16) ssq[(size_t)r * 16 + lane] = lane == 0 ? ss : 0.f; } }
.LBB0_74:
	s_waitcnt lgkmcnt(0)
	global_load_dwordx4 v[18:21], v[4:5], off offset:-2048 nt
	s_waitcnt vmcnt(0)
	v_cvt_pk_bf16_f32 v22, v18, v19
	v_cvt_pk_bf16_f32 v23, v20, v21
	global_store_dwordx2 v[6:7], v[22:23], off offset:-1024 nt
	global_load_dwordx4 v[22:25], v[4:5], off offset:-1024 nt
	s_waitcnt vmcnt(0)
	v_cvt_pk_bf16_f32 v26, v22, v23
	v_cvt_pk_bf16_f32 v27, v24, v25
	global_store_dwordx2 v[6:7], v[26:27], off offset:-512 nt
	global_load_dwordx4 v[26:29], v[4:5], off nt
	s_waitcnt vmcnt(0)
	v_cvt_pk_bf16_f32 v30, v26, v27
	v_cvt_pk_bf16_f32 v31, v28, v29
	global_store_dwordx2 v[6:7], v[30:31], off nt
	global_load_dwordx4 v[30:33], v[4:5], off offset:1024 nt
	v_cmp_lt_i32_e64 s[6:7], v11, v10
	v_mul_f32_e32 v19, v19, v19
	v_mul_f32_e32 v21, v21, v21
	v_fmac_f32_e32 v19, v18, v18
	v_fmac_f32_e32 v21, v20, v20
	v_add_f32_e32 v18, v19, v21
	v_mul_f32_e32 v19, v23, v23
	v_mul_f32_e32 v20, v25, v25
	v_fmac_f32_e32 v19, v22, v22
	v_fmac_f32_e32 v20, v24, v24
	v_add_f32_e32 v19, v19, v20
	v_add_f32_e32 v18, v18, v19
	v_mul_f32_e32 v19, v27, v27
	v_mul_f32_e32 v20, v29, v29
	v_fmac_f32_e32 v19, v26, v26
	v_fmac_f32_e32 v20, v28, v28
	v_add_f32_e32 v19, v19, v20
	v_add_f32_e32 v18, v18, v19
	s_waitcnt vmcnt(0)
	v_mul_f32_e32 v19, v31, v31
	v_mul_f32_e32 v20, v33, v33
	v_fmac_f32_e32 v19, v30, v30
	v_fmac_f32_e32 v20, v32, v32
	v_cndmask_b32_e64 v17, v1, v11, s[6:7]
	v_add_f32_e32 v19, v19, v20
	v_lshlrev_b32_e32 v17, 2, v17
	v_add_f32_e32 v18, v18, v19
	ds_bpermute_b32 v17, v17, v18
	v_cmp_lt_i32_e64 s[6:7], v12, v10
	v_cvt_pk_bf16_f32 v20, v30, v31
	v_cvt_pk_bf16_f32 v21, v32, v33
	global_store_dwordx2 v[6:7], v[20:21], off offset:512 nt
	s_waitcnt lgkmcnt(0)
	v_add_f32_e32 v17, v18, v17
	v_cndmask_b32_e64 v19, v1, v12, s[6:7]
	v_lshlrev_b32_e32 v19, 2, v19
	ds_bpermute_b32 v18, v19, v17
	v_cmp_lt_i32_e64 s[6:7], v13, v10
	s_waitcnt lgkmcnt(0)
	v_add_f32_e32 v17, v17, v18
	v_cndmask_b32_e64 v19, v1, v13, s[6:7]
	v_lshlrev_b32_e32 v19, 2, v19
	ds_bpermute_b32 v18, v19, v17
	v_cmp_lt_i32_e64 s[6:7], v14, v10
	s_waitcnt lgkmcnt(0)
	v_add_f32_e32 v17, v17, v18
	v_cndmask_b32_e64 v19, v1, v14, s[6:7]
	v_lshlrev_b32_e32 v19, 2, v19
	ds_bpermute_b32 v18, v19, v17
	v_cmp_lt_i32_e64 s[6:7], v15, v10
	s_waitcnt lgkmcnt(0)
	v_add_f32_e32 v17, v17, v18
	v_cndmask_b32_e64 v19, v1, v15, s[6:7]
	v_lshlrev_b32_e32 v19, 2, v19
	ds_bpermute_b32 v18, v19, v17
	v_cmp_lt_i32_e64 s[6:7], v16, v10
	s_waitcnt lgkmcnt(0)
	v_add_f32_e32 v17, v17, v18
	v_cndmask_b32_e64 v19, v1, v16, s[6:7]
	v_lshlrev_b32_e32 v18, 2, v19
	ds_bpermute_b32 v18, v18, v17
	s_and_saveexec_b64 s[6:7], vcc
	s_cbranch_execz .LBB0_73
	s_waitcnt lgkmcnt(0)
	v_add_f32_e32 v17, v17, v18
	v_cndmask_b32_e64 v17, 0, v17, s[4:5]
	global_store_dword v[2:3], v17, off
	s_branch .LBB0_73

; #define SGU_LOAD(ch) do { _Pragma("unroll") for (int i = 0; i < 4; ++i) pv[i] = *(const u32x4*)(Z + (size_t)((ch) * 128 + lrow + 32 * i) * ZW + ZSV + g * 128 + cs); } while (0)
; PHASE_FN void sgu_block(const Params& p, unsigned char* lds, int l, int g, int ch0, int nch) {
;     ...
;     const int wid = __builtin_amdgcn_readfirstlane(tid >> 6), lane = tid & 63, lr = lane & 15, q4 = lane >> 4;
;     const bf16_t* __restrict__ Z = (const bf16_t*)(ws + WS_Z); bf16_t* __restrict__ MIX = (bf16_t*)(ws + WS_MIX);
;     const bf16_t* __restrict__ wsb = (const bf16_t*)(ws + WS_WSB) + (size_t)(l * 4 + g) * 128 * 128;
;     bf16_t* wl = (bf16_t*)(lds + L_SW);
;     const int lrow = tid >> 4, cs = (tid & 15) * 8;
; #pragma unroll
;     for (int i = 0; i < 4; ++i) *(u32x4*)(wl + (lrow + 32 * i) * SP + cs) = *(const u32x4*)(wsb + (size_t)(lrow + 32 * i) * 128 + cs);
;     const float* ngp = p.sgu_norm_g + (size_t)l * 512 + g * 128 + cs; const f32x4 g0 = *(const f32x4*)ngp, g1 = *(const f32x4*)(ngp + 4);
;     float bs[8];
; #pragma unroll
;     for (int pb = 0; pb < 8; ++pb) bs[pb] = p.b_s[(size_t)l * 512 + g * 128 + 16 * pb + lr];
;     const int ocol = g * 128 + 16 * wid + 4 * q4;
;     u32x4 pv[4];
;     ...
;     SGU_LOAD(ch0);
.LBB0_252:
	v_mov_b32_e32 v6, v206
	s_lshl_b32 s10, s9, 15
	s_add_i32 s10, s10, s4
	v_lshlrev_b32_e32 v0, 3, v6
	s_add_u32 s10, s91, s10
	v_readlane_b32 s11, v248, 34
	v_ashrrev_i32_e32 v24, 4, v6
	v_and_b32_e32 v40, 0x78, v0
	s_addc_u32 s11, s11, 0
	v_lshlrev_b32_e32 v152, 1, v40
	v_ashrrev_i32_e32 v25, 31, v24
	v_lshl_add_u64 v[0:1], s[10:11], 0, v[152:153]
	v_lshlrev_b64 v[2:3], 8, v[24:25]
	v_lshl_add_u64 v[4:5], v[0:1], 0, v[2:3]
	global_load_dwordx4 v[0:3], v[4:5], off
	s_movk_i32 s10, 0x110
	v_mul_lo_u32 v41, v24, s10
	v_add3_u32 v7, 0, v152, v41
	s_movk_i32 s10, 0x4000
	s_lshl_b32 s76, s9, 7
	v_and_b32_e32 v76, 15, v6
	v_lshlrev_b32_e32 v8, 2, v76
	v_readfirstlane_b32 s14, v6
	v_bfe_u32 v28, v6, 4, 2
	v_mov_b64_e32 v[20:21], s[60:61]
	v_and_b32_e32 v27, 64, v209
	v_xor_b32_e32 v25, 1, v209
	v_add_u32_e32 v27, 64, v27
	v_mul_u32_u24_e32 v89, 0x880, v28
	v_add_u32_e32 v90, s25, v24
	v_add_u32_e32 v91, s25, v76
	s_waitcnt vmcnt(0)
	ds_write_b128 v7, v[0:3]
	v_add_co_u32_e32 v0, vcc, s35, v4
	s_nop 1
	v_addc_co_u32_e32 v1, vcc, 0, v5, vcc
	global_load_dwordx4 v[0:3], v[0:1], off
	s_waitcnt vmcnt(0)
	ds_write_b128 v7, v[0:3] offset:8704
	v_add_co_u32_e32 v0, vcc, s10, v4
	s_movk_i32 s10, 0x6000
	s_nop 0
	v_addc_co_u32_e32 v1, vcc, 0, v5, vcc
	global_load_dwordx4 v[0:3], v[0:1], off
	s_waitcnt vmcnt(0)
	ds_write_b128 v7, v[0:3] offset:17408
	v_add_co_u32_e32 v0, vcc, s10, v4
	s_lshl_b64 s[10:11], s[76:77], 2
	s_nop 0
	v_addc_co_u32_e32 v1, vcc, 0, v5, vcc
	global_load_dwordx4 v[0:3], v[0:1], off
	s_add_u32 s12, s5, s10
	s_addc_u32 s13, s6, s11
	s_add_u32 s10, s7, s10
	v_lshlrev_b32_e32 v4, 2, v40
	s_addc_u32 s11, s8, s11
	s_waitcnt vmcnt(0)
	ds_write_b128 v7, v[0:3] offset:26112
	global_load_dwordx4 v[0:3], v4, s[12:13]
	s_nop 0
	global_load_dwordx4 v[4:7], v4, s[12:13] offset:16
	s_nop 0
	global_load_dword v77, v8, s[10:11]
	global_load_dword v78, v8, s[10:11] offset:64
	global_load_dword v79, v8, s[10:11] offset:128
	global_load_dword v80, v8, s[10:11] offset:192
	global_load_dword v81, v8, s[10:11] offset:256
	global_load_dword v82, v8, s[10:11] offset:320
	global_load_dword v83, v8, s[10:11] offset:384
	global_load_dword v84, v8, s[10:11] offset:448
	v_readlane_b32 s11, v247, 35
	s_ashr_i32 s10, s14, 2
	s_and_b32 s10, s10, -16
	v_add_u32_e32 v22, s11, v24
	v_mad_i64_i32 v[8:9], s[12:13], v22, s1, v[20:21]
	s_lshl_b32 s12, s9, 8
	s_mov_b32 s13, s77
	v_lshl_add_u64 v[8:9], v[8:9], 0, s[12:13]
	v_add_u32_e32 v12, 32, v22
	v_lshl_add_u64 v[8:9], v[8:9], 0, v[152:153]
	s_movk_i32 s11, 0x1000
	v_mad_i64_i32 v[12:13], s[14:15], v12, s1, v[20:21]
	v_add_co_u32_e32 v8, vcc, s11, v8
	v_lshl_add_u64 v[12:13], v[12:13], 0, s[12:13]
	v_add_u32_e32 v16, 64, v22
	v_addc_co_u32_e32 v9, vcc, 0, v9, vcc
	v_lshl_add_u64 v[12:13], v[12:13], 0, v[152:153]
	v_mad_i64_i32 v[16:17], s[14:15], v16, s1, v[20:21]
	v_add_co_u32_e32 v12, vcc, s11, v12
	v_lshl_add_u64 v[16:17], v[16:17], 0, s[12:13]
	v_add_u32_e32 v22, 0x60, v22
	v_addc_co_u32_e32 v13, vcc, 0, v13, vcc
	v_lshl_add_u64 v[16:17], v[16:17], 0, v[152:153]
	v_mad_i64_i32 v[20:21], s[14:15], v22, s1, v[20:21]
	v_add_co_u32_e32 v16, vcc, s11, v16
	v_lshl_add_u64 v[20:21], v[20:21], 0, s[12:13]
	s_nop 0
	v_addc_co_u32_e32 v17, vcc, 0, v17, vcc
	v_lshl_add_u64 v[20:21], v[20:21], 0, v[152:153]
	v_add_co_u32_e32 v20, vcc, s11, v20
	global_load_dwordx4 v[8:11], v[8:9], off offset:512 nt
	s_nop 0
	v_addc_co_u32_e32 v21, vcc, 0, v21, vcc
	global_load_dwordx4 v[12:15], v[12:13], off offset:512 nt
	v_cmp_lt_i32_e32 vcc, v25, v27
	global_load_dwordx4 v[16:19], v[16:17], off offset:512 nt
	s_add_i32 s11, s10, s76
	global_load_dwordx4 v[20:23], v[20:21], off offset:512 nt
	v_cndmask_b32_e32 v25, v209, v25, vcc
	v_lshlrev_b32_e32 v85, 2, v25
	v_xor_b32_e32 v25, 2, v209
	v_cmp_lt_i32_e32 vcc, v25, v27
	v_lshl_or_b32 v26, v28, 2, s11
	s_lshl_b32 s76, s76, 1
	v_cndmask_b32_e32 v25, v209, v25, vcc
	v_lshlrev_b32_e32 v86, 2, v25
	v_xor_b32_e32 v25, 4, v209
	v_cmp_lt_i32_e32 vcc, v25, v27
	v_readlane_b32 s11, v246, 37
	s_mov_b32 s12, 0
	v_cndmask_b32_e32 v25, v209, v25, vcc
	v_lshlrev_b32_e32 v87, 2, v25
	v_xor_b32_e32 v25, 8, v209
	v_cmp_lt_i32_e32 vcc, v25, v27
	v_ashrrev_i32_e32 v27, 31, v26
	v_lshl_add_u64 v[42:43], v[26:27], 1, s[60:61]
	v_cndmask_b32_e32 v25, v209, v25, vcc
	v_lshlrev_b32_e32 v88, 2, v25
	v_lshl_add_u32 v25, v28, 4, 0
	v_mul_u32_u24_e32 v28, 0x110, v76
	v_add_u32_e32 v92, v25, v28
	v_lshlrev_b64 v[44:45], 1, v[26:27]
	s_mov_b32 s13, 0
	s_branch .LBB0_254
